# v114 + mixer conv queue sharded into 8 per-XCD heads (items dealt by item % 8), so the returning atomics no longer pile up on one address
# baseline (speedup 1.0000x reference)
; __device__ __forceinline__ void p_mixer(const Args& a, int l, LAS unsigned char* lds, int tid, int lane, int wave, int bid, int G) {
;     ...
;         if (threadIdx.x == 0) slot[0] = __hip_atomic_fetch_add(head, 1u, __ATOMIC_RELAXED, __HIP_MEMORY_SCOPE_AGENT);
;         __syncthreads();
;         const int q = (int)slot[0];
;         __syncthreads();
;         if (q >= N_AS + N_CV) { queue_empty = true; continue; }
.Lq_dyn128:
	s_and_b32 s6, s71, 7
	s_lshl_b32 s7, s6, 6
	v_readlane_b32 s8, v255, 21
	s_nop 3
	s_lshl_b32 s8, s8, 9
	s_add_i32 s7, s7, s8
	s_add_u32 s2, s78, 0x1703c00
	s_addc_u32 s3, s79, 0
	s_add_u32 s2, s2, s7
	s_addc_u32 s3, s3, 0
	global_atomic_add v1, v173, v1, s[2:3] sc0
	s_waitcnt vmcnt(0)
	v_cmp_gt_u32_e32 vcc, 34, v1
	v_lshl_add_u32 v1, v1, 3, s6
	v_add_u32_e32 v1, 0x80, v1
	v_mov_b32_e32 v241, 0x190
	s_nop 1
	v_cndmask_b32_e32 v1, v241, v1, vcc
	s_branch .LBB0_450
